# ctx_gemm<2> (context rows of the FFN-down GEMM): K-chunk granular 4-stage LDS ring, three 32 KiB chunks in flight instead of one super-chunk
# baseline (speedup 1.0000x reference)
.LBB1_522:
	s_lshl_b32 s25, s10, 15
	s_mov_b32 s24, s30
	s_add_i32 s30, s25, s7
	s_mov_b32 s31, m0
	s_mov_b32 m0, s30
	s_nop 0
	global_load_lds_dwordx4 v[212:213], off
	s_mov_b32 m0, s31
	s_addk_i32 s30, 0x2000
	v_lshl_add_u64 v[66:67], v[212:213], 0, s[48:49]
	s_mov_b32 s31, m0
	s_mov_b32 m0, s30
	s_nop 0
	global_load_lds_dwordx4 v[66:67], off
	s_mov_b32 m0, s31
	v_lshl_add_u64 v[64:65], v[210:211], 0, s[26:27]
	s_add_i32 s25, s25, s9
	s_mov_b32 s30, m0
	s_mov_b32 m0, s25
	s_nop 0
	global_load_lds_dwordx4 v[64:65], off
	s_mov_b32 m0, s30
	s_addk_i32 s25, 0x2000
	s_mov_b64 s[30:31], 0x88000
	v_lshl_add_u64 v[64:65], v[64:65], 0, s[30:31]
	s_mov_b32 s30, m0
	s_mov_b32 m0, s25
	s_nop 0
	global_load_lds_dwordx4 v[64:65], off
	s_mov_b32 m0, s30
	s_lshl_b32 s25, s11, 15
	s_add_i32 s25, s25, 0
	v_add_u32_e32 v64, s25, v248
	v_add_u32_e32 v65, v64, v244
	v_add_u32_e32 v66, v64, v245
	v_add_u32_e32 v67, v64, v246
	v_add_u32_e32 v64, v64, v247
	ds_read_b128 v[166:169], v65
	ds_read_b128 v[174:177], v65 offset:4096
	ds_read_b128 v[170:173], v66
	ds_read_b128 v[162:165], v66 offset:4096
	ds_read_b128 v[158:161], v67
	ds_read_b128 v[154:157], v67 offset:4096
	ds_read_b128 v[150:153], v64
	ds_read_b128 v[146:149], v64 offset:4096
	v_cmp_neq_f32_e64 s[36:37], 0, v209
	v_xor_b32_e32 v64, 0x80000000, v209
	s_mov_b64 vcc, s[36:37]
	s_cbranch_vccz .LBB1_532
	v_mov_b32_e32 v65, v64
	v_mov_b32_e32 v66, v64
	v_mov_b32_e32 v67, v64
	v_mov_b32_e32 v68, v64
	v_mov_b32_e32 v69, v64
	v_mov_b32_e32 v70, v64
	v_mov_b32_e32 v71, v64
	v_mov_b32_e32 v72, v64
	v_mov_b32_e32 v73, v64
	v_mov_b32_e32 v74, v64
	v_mov_b32_e32 v75, v64
	v_mov_b32_e32 v76, v64
	v_mov_b32_e32 v77, v64
	v_mov_b32_e32 v78, v64
	v_mov_b32_e32 v79, v64
	v_mov_b64_e32 v[110:111], v[78:79]
	v_mov_b64_e32 v[108:109], v[76:77]
	v_mov_b64_e32 v[106:107], v[74:75]
	v_mov_b64_e32 v[104:105], v[72:73]
	v_mov_b64_e32 v[102:103], v[70:71]
	v_mov_b64_e32 v[100:101], v[68:69]
	v_mov_b64_e32 v[98:99], v[66:67]
	v_mov_b64_e32 v[96:97], v[64:65]
	s_waitcnt lgkmcnt(7)
	v_mfma_f32_32x32x16_bf16 v[80:95], v[166:169], v[126:129], v[64:79]
	s_waitcnt lgkmcnt(6)
	v_mfma_f32_32x32x16_bf16 v[96:111], v[174:177], v[126:129], v[96:111]
	s_waitcnt lgkmcnt(5)
	v_mfma_f32_32x32x16_bf16 v[80:95], v[170:173], v[122:125], v[80:95]
	s_waitcnt lgkmcnt(4)
	v_mfma_f32_32x32x16_bf16 v[96:111], v[162:165], v[122:125], v[96:111]
	s_waitcnt lgkmcnt(3)
	v_mfma_f32_32x32x16_bf16 v[80:95], v[158:161], v[118:121], v[80:95]
	s_waitcnt lgkmcnt(2)
	v_mfma_f32_32x32x16_bf16 v[96:111], v[154:157], v[118:121], v[96:111]
	s_waitcnt lgkmcnt(1)
	v_mfma_f32_32x32x16_bf16 v[80:95], v[150:153], v[114:117], v[80:95]
	s_waitcnt lgkmcnt(0)
	v_mfma_f32_32x32x16_bf16 v[96:111], v[146:149], v[114:117], v[96:111]
	s_cbranch_execnz .LBB1_525
.LBB1_524:
	s_waitcnt lgkmcnt(7)
	v_mfma_f32_32x32x16_bf16 v[80:95], v[166:169], v[126:129], 0
	s_waitcnt lgkmcnt(6)
	v_mfma_f32_32x32x16_bf16 v[96:111], v[174:177], v[126:129], 0
	s_waitcnt lgkmcnt(5)
	v_mfma_f32_32x32x16_bf16 v[80:95], v[170:173], v[122:125], v[80:95]
	s_waitcnt lgkmcnt(4)
	v_mfma_f32_32x32x16_bf16 v[96:111], v[162:165], v[122:125], v[96:111]
	s_waitcnt lgkmcnt(3)
	v_mfma_f32_32x32x16_bf16 v[80:95], v[158:161], v[118:121], v[80:95]
	s_waitcnt lgkmcnt(2)
	v_mfma_f32_32x32x16_bf16 v[96:111], v[154:157], v[118:121], v[96:111]
	s_waitcnt lgkmcnt(1)
	v_mfma_f32_32x32x16_bf16 v[80:95], v[150:153], v[114:117], v[80:95]
	s_waitcnt lgkmcnt(0)
	v_mfma_f32_32x32x16_bf16 v[96:111], v[146:149], v[114:117], v[96:111]

.LBB1_530:
	v_add3_u32 v64, s25, v243, v224
	ds_read_b128 v[190:193], v64 offset:16384
	ds_read_b128 v[186:189], v64 offset:20480
	ds_read_b128 v[182:185], v64 offset:24576
	ds_read_b128 v[142:145], v64 offset:28672
	s_waitcnt vmcnt(0) lgkmcnt(0)
	s_barrier
	s_add_u32 s26, s26, 0x80
	s_addc_u32 s27, s27, 0
	v_cvt_pk_bf16_f32 v178, v80, v81
	v_cvt_pk_bf16_f32 v179, v82, v83
	v_cvt_pk_bf16_f32 v180, v84, v85
	v_cvt_pk_bf16_f32 v181, v86, v87
	v_cvt_pk_bf16_f32 v138, v88, v89
	v_cvt_pk_bf16_f32 v139, v90, v91
	v_cvt_pk_bf16_f32 v140, v92, v93
	v_cvt_pk_bf16_f32 v141, v94, v95
	v_cvt_pk_bf16_f32 v134, v96, v97
	v_cvt_pk_bf16_f32 v135, v98, v99
	v_cvt_pk_bf16_f32 v136, v100, v101
	v_cvt_pk_bf16_f32 v137, v102, v103
	v_cvt_pk_bf16_f32 v130, v104, v105
	v_cvt_pk_bf16_f32 v131, v106, v107
	v_cvt_pk_bf16_f32 v132, v108, v109
	v_cvt_pk_bf16_f32 v133, v110, v111
	v_add_f32_e32 v238, v66, v238
	s_cmpk_eq_i32 s26, 0x2100
	v_lshl_add_u64 v[212:213], v[212:213], 0, s[34:35]
	s_cbranch_scc1 .LBB1_534
	s_mov_b32 s30, s11
	s_mov_b32 s11, s10
	s_mov_b32 s10, s24
	s_branch .LBB1_522

.LBB1_533:
	s_branch .LBB1_528
.LBB1_534:
	ds_read_b128 v[158:161], v249 offset:32768
	ds_read_b128 v[174:177], v249 offset:36864
	ds_read_b128 v[170:173], v250 offset:32768
	ds_read_b128 v[166:169], v250 offset:36864
	ds_read_b128 v[162:165], v251 offset:32768
	ds_read_b128 v[154:157], v251 offset:36864
	ds_read_b128 v[150:153], v252 offset:32768
	ds_read_b128 v[146:149], v252 offset:36864
	v_cmp_neq_f32_e64 s[36:37], 0, v209
	v_xor_b32_e32 v64, 0x80000000, v209
	s_mov_b64 vcc, s[36:37]
	s_cbranch_vccz .LBB1_549
	v_mov_b32_e32 v65, v64
	v_mov_b32_e32 v66, v64
	v_mov_b32_e32 v67, v64
	v_mov_b32_e32 v68, v64
	v_mov_b32_e32 v69, v64
	v_mov_b32_e32 v70, v64
	v_mov_b32_e32 v71, v64
	v_mov_b32_e32 v72, v64
	v_mov_b32_e32 v73, v64
	v_mov_b32_e32 v74, v64
	v_mov_b32_e32 v75, v64
	v_mov_b32_e32 v76, v64
	v_mov_b32_e32 v77, v64
	v_mov_b32_e32 v78, v64
	v_mov_b32_e32 v79, v64
	v_mov_b64_e32 v[110:111], v[78:79]
	v_mov_b64_e32 v[108:109], v[76:77]
	v_mov_b64_e32 v[106:107], v[74:75]
	v_mov_b64_e32 v[104:105], v[72:73]
	v_mov_b64_e32 v[102:103], v[70:71]
	v_mov_b64_e32 v[100:101], v[68:69]
	v_mov_b64_e32 v[98:99], v[66:67]
	v_mov_b64_e32 v[96:97], v[64:65]
	s_waitcnt lgkmcnt(7)
	v_mfma_f32_32x32x16_bf16 v[80:95], v[158:161], v[126:129], v[64:79]
	s_waitcnt lgkmcnt(6)
	v_mfma_f32_32x32x16_bf16 v[96:111], v[174:177], v[126:129], v[96:111]
	s_waitcnt lgkmcnt(5)
	v_mfma_f32_32x32x16_bf16 v[80:95], v[170:173], v[122:125], v[80:95]
	s_waitcnt lgkmcnt(4)
	v_mfma_f32_32x32x16_bf16 v[96:111], v[166:169], v[122:125], v[96:111]
	s_waitcnt lgkmcnt(3)
	v_mfma_f32_32x32x16_bf16 v[80:95], v[162:165], v[118:121], v[80:95]
	s_waitcnt lgkmcnt(2)
	v_mfma_f32_32x32x16_bf16 v[96:111], v[154:157], v[118:121], v[96:111]
	s_waitcnt lgkmcnt(1)
	v_mfma_f32_32x32x16_bf16 v[80:95], v[150:153], v[114:117], v[80:95]
	s_waitcnt lgkmcnt(0)
	v_mfma_f32_32x32x16_bf16 v[96:111], v[146:149], v[114:117], v[96:111]
	s_movk_i32 s25, 0x120
	s_cbranch_execnz .LBB1_537

.LBB1_1264:
	s_lshl_b32 s10, s6, 6
	s_and_b32 s10, s10, 0x1c0
	s_ashr_i32 s24, s6, 3
	s_bfe_u32 s9, s6, 0x20003
	s_or_b32 s72, s10, 0x2000
	s_and_b32 s10, s24, 0x3fffffc
	s_or_b32 s10, s10, s9
	s_lshl_b32 s18, s10, 6
	v_readlane_b32 s10, v255, 0
	v_readlane_b32 s11, v255, 1
	v_lshl_add_u64 v[0:1], s[72:73], 0, v[8:9]
	s_movk_i32 s25, 0x2c00
	v_mov_b64_e32 v[2:3], s[10:11]
	s_ashr_i32 s19, s18, 31
	v_mad_u64_u32 v[2:3], s[10:11], v0, s25, v[2:3]
	v_mad_i32_i24 v3, v1, s25, v3
	v_mov_b32_e32 v19, v113
	v_lshl_add_u64 v[6:7], s[18:19], 0, v[8:9]
	v_mov_b64_e32 v[20:21], s[38:39]
	s_mov_b32 m0, s1
	v_lshl_add_u64 v[0:1], v[2:3], 0, v[112:113]
	v_lshl_add_u64 v[2:3], v[2:3], 0, v[18:19]
	v_mad_u64_u32 v[20:21], s[10:11], v6, s25, v[20:21]
	s_waitcnt vmcnt(0) lgkmcnt(0)
	s_barrier
	v_lshl_add_u64 v[4:5], v[2:3], 0, s[30:31]
	v_mad_i32_i24 v21, v7, s25, v21
	global_load_lds_dwordx4 v[0:1], off
	s_add_i32 m0, s1, 0x400
	v_lshl_add_u64 v[6:7], v[20:21], 0, v[112:113]
	v_lshl_add_u64 v[20:21], v[20:21], 0, v[18:19]
	global_load_lds_dwordx4 v[4:5], off
	s_add_i32 m0, s1, 0x4000
	v_lshl_add_u64 v[22:23], v[20:21], 0, s[30:31]
	global_load_lds_dwordx4 v[6:7], off
	s_add_i32 m0, s1, 0x4400
	s_mov_b64 s[10:11], 0x100
	global_load_lds_dwordx4 v[22:23], off
	v_lshl_add_u64 v[0:1], v[0:1], 0, s[10:11]
	s_add_i32 m0, s1, 0x8000
	s_bfe_u32 s19, s7, 0x30006
	global_load_lds_dwordx4 v[0:1], off
	v_lshl_add_u64 v[0:1], v[2:3], 0, s[36:37]
	s_add_i32 m0, s1, 0x8400
	s_lshl_b32 s9, s9, 6
	global_load_lds_dwordx4 v[0:1], off
	v_lshl_add_u64 v[0:1], v[6:7], 0, s[10:11]
	s_add_i32 m0, s1, 0xc000
	v_mad_u64_u32 v[22:23], s[10:11], s19, v233, v[12:13]
	global_load_lds_dwordx4 v[0:1], off
	v_lshl_add_u64 v[0:1], v[20:21], 0, s[36:37]
	s_add_i32 m0, s1, 0xc400
	v_mad_u64_u32 v[20:21], s[10:11], s19, v233, v[10:11]
	global_load_lds_dwordx4 v[0:1], off
	s_lshl_b32 s10, s24, 6
	s_and_b32 s10, s10, 0xffffff00
	s_or_b32 s10, s10, s9
	s_ashr_i32 s11, s10, 31
	s_waitcnt vmcnt(0)
	s_barrier
	v_lshl_add_u64 v[0:1], v[8:9], 0, s[10:11]
	v_mad_u64_u32 v[24:25], s[10:11], v0, s25, v[14:15]
	v_mad_u64_u32 v[26:27], s[10:11], v0, s25, v[16:17]
	v_mov_b32_e32 v0, 0
	v_mad_i32_i24 v25, v1, s25, v25
	v_mad_i32_i24 v27, v1, s25, v27
	v_mov_b32_e32 v1, v0
	v_mov_b32_e32 v2, v0
	v_mov_b32_e32 v3, v0
	v_mov_b32_e32 v4, v0
	v_mov_b32_e32 v5, v0
	v_mov_b32_e32 v6, v0
	v_mov_b32_e32 v7, v0
	s_mov_b64 s[24:25], 0x28b00000
	v_lshl_add_u64 v[60:61], v[20:21], 0, s[24:25]
	s_mov_b64 s[24:25], 0x28b0b000
	v_lshl_add_u64 v[62:63], v[22:23], 0, s[24:25]
	s_mov_b64 s[24:25], 0x2f900000
	v_lshl_add_u64 v[64:65], v[24:25], 0, s[24:25]
	s_mov_b64 s[24:25], 0x2f90b000
	v_lshl_add_u64 v[66:67], v[26:27], 0, s[24:25]
	s_mov_b64 s[26:27], 0x200
	s_add_i32 s9, s1, 0x10000
	v_lshl_add_u64 v[104:105], v[60:61], 0, s[26:27]
	s_mov_b32 m0, s9
	s_nop 0
	global_load_lds_dwordx4 v[104:105], off
	v_lshl_add_u64 v[104:105], v[62:63], 0, s[26:27]
	s_add_i32 m0, s9, 0x400
	s_nop 0
	global_load_lds_dwordx4 v[104:105], off
	v_lshl_add_u64 v[104:105], v[64:65], 0, s[26:27]
	s_add_i32 m0, s9, 0x4000
	s_nop 0
	global_load_lds_dwordx4 v[104:105], off
	v_lshl_add_u64 v[104:105], v[66:67], 0, s[26:27]
	s_add_i32 m0, s9, 0x4400
	s_nop 0
	global_load_lds_dwordx4 v[104:105], off
	s_mov_b64 s[26:27], 0x300
	s_mov_b32 s10, 0
.Lcg2_loop:
	s_cmp_gt_u32 s10, 40
	s_cbranch_scc1 .Lcg2_nodma
	s_add_i32 s9, s10, 3
	s_and_b32 s9, s9, 3
	s_lshl_b32 s9, s9, 15
	s_add_i32 s9, s9, s1
	v_lshl_add_u64 v[104:105], v[60:61], 0, s[26:27]
	s_mov_b32 m0, s9
	s_nop 0
	global_load_lds_dwordx4 v[104:105], off
	v_lshl_add_u64 v[104:105], v[62:63], 0, s[26:27]
	s_add_i32 m0, s9, 0x400
	s_nop 0
	global_load_lds_dwordx4 v[104:105], off
	v_lshl_add_u64 v[104:105], v[64:65], 0, s[26:27]
	s_add_i32 m0, s9, 0x4000
	s_nop 0
	global_load_lds_dwordx4 v[104:105], off
	v_lshl_add_u64 v[104:105], v[66:67], 0, s[26:27]
	s_add_i32 m0, s9, 0x4400
	s_nop 0
	global_load_lds_dwordx4 v[104:105], off
	s_add_u32 s26, s26, 0x100
	s_addc_u32 s27, s27, 0
.Lcg2_nodma:
	s_and_b32 s9, s10, 3
	s_lshl_b32 s9, s9, 15
	v_add_u32_e32 v106, s9, v29
	s_add_i32 s11, s9, s5
	v_add_u32_e32 v107, s11, v30
	v_add_u32_e32 v108, v106, v33
	v_add_u32_e32 v109, v107, v33
	ds_read_b128 v[40:43], v108
	ds_read_b128 v[44:47], v109 offset:16384
	ds_read_b128 v[48:51], v109 offset:20480
	v_add_u32_e32 v108, v106, v34
	v_add_u32_e32 v109, v107, v34
	ds_read_b128 v[68:71], v108
	ds_read_b128 v[72:75], v109 offset:16384
	ds_read_b128 v[76:79], v109 offset:20480
	v_add_u32_e32 v108, v106, v35
	v_add_u32_e32 v109, v107, v35
	ds_read_b128 v[80:83], v108
	ds_read_b128 v[84:87], v109 offset:16384
	ds_read_b128 v[88:91], v109 offset:20480
	v_add_u32_e32 v108, v106, v32
	v_add_u32_e32 v109, v107, v32
	ds_read_b128 v[92:95], v108
	ds_read_b128 v[96:99], v109 offset:16384
	ds_read_b128 v[100:103], v109 offset:20480
	s_waitcnt lgkmcnt(9)
	v_mfma_f32_16x16x32_bf16 v[0:3], v[44:47], v[40:43], v[0:3]
	v_mfma_f32_16x16x32_bf16 v[4:7], v[48:51], v[40:43], v[4:7]
	s_waitcnt lgkmcnt(6)
	v_mfma_f32_16x16x32_bf16 v[0:3], v[72:75], v[68:71], v[0:3]
	v_mfma_f32_16x16x32_bf16 v[4:7], v[76:79], v[68:71], v[4:7]
	s_waitcnt lgkmcnt(3)
	v_mfma_f32_16x16x32_bf16 v[0:3], v[84:87], v[80:83], v[0:3]
	v_mfma_f32_16x16x32_bf16 v[4:7], v[88:91], v[80:83], v[4:7]
	s_waitcnt lgkmcnt(0)
	v_mfma_f32_16x16x32_bf16 v[0:3], v[96:99], v[92:95], v[0:3]
	v_mfma_f32_16x16x32_bf16 v[4:7], v[100:103], v[92:95], v[4:7]
	s_cmp_gt_u32 s10, 40
	s_cbranch_scc1 .Lcg2_tail
	s_waitcnt vmcnt(8)
	s_branch .Lcg2_bar

.Lcg2_bar:
	s_barrier
	s_add_i32 s10, s10, 1
	s_cmp_lt_u32 s10, 42
	s_cbranch_scc1 .Lcg2_loop
	v_add_u32_e32 v19, v37, v33
	ds_read_b128 v[20:23], v19 offset:16384
	v_add_u32_e32 v24, v38, v33
	ds_read_b128 v[24:27], v24
	ds_read_b128 v[40:43], v19 offset:20480
	v_add_u32_e32 v44, v38, v34
	v_add_u32_e32 v19, v37, v34
	ds_read_b128 v[44:47], v44
	s_waitcnt lgkmcnt(0)
	v_mfma_f32_16x16x32_bf16 v[4:7], v[40:43], v[24:27], v[4:7]
	v_add_u32_e32 v40, v37, v35
	v_add_u32_e32 v41, v38, v35
	v_add_u32_e32 v52, v36, v34
	v_mfma_f32_16x16x32_bf16 v[0:3], v[20:23], v[24:27], v[0:3]
	ds_read_b128 v[20:23], v19 offset:16384
	ds_read_b128 v[48:51], v19 offset:20480
	ds_read_b128 v[24:27], v40 offset:16384
	v_add_u32_e32 v19, v37, v32
	s_waitcnt lgkmcnt(0)
	v_mfma_f32_16x16x32_bf16 v[0:3], v[20:23], v[44:47], v[0:3]
	ds_read_b128 v[20:23], v40 offset:20480
	ds_read_b128 v[40:43], v41
	v_add_u32_e32 v53, v31, v33
	v_add_u32_e32 v60, v31, v35
	v_mfma_f32_16x16x32_bf16 v[4:7], v[48:51], v[44:47], v[4:7]
	ds_read_b128 v[44:47], v19 offset:16384
	v_add_u32_e32 v48, v38, v32
	ds_read_b128 v[48:51], v48
	s_waitcnt lgkmcnt(0)
	v_mfma_f32_16x16x32_bf16 v[0:3], v[24:27], v[40:43], v[0:3]
	ds_read_b128 v[24:27], v19 offset:20480
	v_add_u32_e32 v19, v31, v32
	s_add_i32 s6, s6, s33
	v_mfma_f32_16x16x32_bf16 v[4:7], v[20:23], v[40:43], v[4:7]
	ds_read_b128 v[20:23], v52
	ds_read_b128 v[40:43], v53 offset:16384
	v_add_u32_e32 v52, v36, v33
	s_add_i32 s7, s7, s94
	v_mfma_f32_16x16x32_bf16 v[0:3], v[44:47], v[48:51], v[0:3]
	ds_read_b128 v[44:47], v53 offset:20480
	ds_read_b128 v[52:55], v52
	s_cmpk_gt_i32 s6, 0xff
	s_waitcnt lgkmcnt(0)
	v_mfma_f32_16x16x32_bf16 v[4:7], v[24:27], v[48:51], v[4:7]
	v_add_u32_e32 v48, v31, v34
	ds_read_b128 v[24:27], v48 offset:20480
	ds_read_b128 v[48:51], v48 offset:16384
	v_mfma_f32_16x16x32_bf16 v[0:3], v[40:43], v[52:55], v[0:3]
	ds_read_b128 v[40:43], v19 offset:20480
	ds_read_b128 v[56:59], v19 offset:16384
	v_add_u32_e32 v19, v36, v32
	v_mfma_f32_16x16x32_bf16 v[4:7], v[44:47], v[52:55], v[4:7]
	ds_read_b128 v[44:47], v19
	ds_read_b128 v[52:55], v60 offset:16384
	v_add_u32_e32 v19, v36, v35
	s_waitcnt lgkmcnt(0)
	v_mfma_f32_16x16x32_bf16 v[0:3], v[48:51], v[20:23], v[0:3]
	ds_read_b128 v[48:51], v60 offset:20480
	ds_read_b128 v[60:63], v19
	s_waitcnt vmcnt(0) lgkmcnt(0)
	s_barrier
	v_mfma_f32_16x16x32_bf16 v[4:7], v[24:27], v[20:23], v[4:7]
	v_add_u32_e32 v20, s72, v28
	v_ashrrev_i32_e32 v21, 31, v20
	v_lshlrev_b64 v[20:21], 12, v[20:21]
	v_or_b32_e32 v24, s18, v39
	v_ashrrev_i32_e32 v25, 31, v24
	v_lshl_add_u64 v[20:21], s[12:13], 0, v[20:21]
	v_lshl_add_u64 v[26:27], v[24:25], 1, v[20:21]
	global_load_dwordx2 v[64:65], v[26:27], off
	v_lshl_add_u64 v[20:21], v[24:25], 2, s[16:17]
	global_load_dwordx4 v[20:23], v[20:21], off
	s_waitcnt lgkmcnt(0)
	v_mfma_f32_16x16x32_bf16 v[0:3], v[52:55], v[60:63], v[0:3]
	v_or_b32_e32 v24, 16, v24
	v_ashrrev_i32_e32 v25, 31, v24
	v_lshl_add_u64 v[24:25], v[24:25], 2, s[16:17]
	v_mfma_f32_16x16x32_bf16 v[0:3], v[56:59], v[44:47], v[0:3]
	s_waitcnt vmcnt(0)
	v_lshlrev_b32_e32 v52, 16, v65
	v_mfma_f32_16x16x32_bf16 v[4:7], v[48:51], v[60:63], v[4:7]
	v_lshlrev_b32_e32 v50, 16, v64
	v_and_b32_e32 v51, 0xffff0000, v64
	v_and_b32_e32 v53, 0xffff0000, v65
	s_nop 1
	v_pk_fma_f32 v[2:3], v[2:3], v[22:23], v[52:53]
	v_pk_fma_f32 v[0:1], v[0:1], v[20:21], v[50:51]
	global_load_dwordx2 v[48:49], v[26:27], off offset:32
	v_cvt_pk_bf16_f32 v0, v0, v1
	v_cvt_pk_bf16_f32 v1, v2, v3
	global_store_dwordx2 v[26:27], v[0:1], off
	global_load_dwordx4 v[0:3], v[24:25], off
	v_mfma_f32_16x16x32_bf16 v[4:7], v[40:43], v[44:47], v[4:7]
	s_waitcnt vmcnt(2)
	v_lshlrev_b32_e32 v20, 16, v48
	v_and_b32_e32 v21, 0xffff0000, v48
	v_lshlrev_b32_e32 v22, 16, v49
	v_and_b32_e32 v23, 0xffff0000, v49
	s_waitcnt vmcnt(0)
	s_nop 1
	v_pk_fma_f32 v[2:3], v[6:7], v[2:3], v[22:23]
	v_pk_fma_f32 v[0:1], v[4:5], v[0:1], v[20:21]
	s_nop 0
	v_cvt_pk_bf16_f32 v0, v0, v1
	v_cvt_pk_bf16_f32 v1, v2, v3
	global_store_dwordx2 v[26:27], v[0:1], off offset:32
	s_cbranch_scc0 .LBB1_1264
